# S5 scan: plain fma recurrence chains replacing packed ops; burst LDS reads before output MFMAs
# speedup vs baseline: 1.0062x; 1.0062x over previous
.LBB0_99:
	s_or_b64 exec, exec, s[20:21]
	s_sub_i32 s20, s34, 32
	v_add_u32_e32 v0, 32, v210
	v_mov_b32_e32 v2, s20
	v_cndmask_b32_e64 v0, v0, v2, s[40:41]
	s_waitcnt lgkmcnt(0)
	ds_read_b128 v[14:17], v208
	ds_read_b128 v[30:33], v208 offset:4352
	ds_read_b128 v[18:21], v208 offset:64
	ds_read_b128 v[34:37], v208 offset:4416
	ds_read_b128 v[22:25], v208 offset:128
	ds_read_b128 v[38:41], v208 offset:4480
	ds_read_b128 v[26:29], v208 offset:192
	ds_read_b128 v[42:45], v208 offset:4544
	s_movk_i32 s20, 0x3000
	s_add_i32 s28, s28, 1
	s_add_i32 s34, s34, 16
	v_add_u32_e32 v210, -16, v210
	v_mov_b32_e32 v182, v179
	v_mov_b32_e32 v180, v177
	s_waitcnt lgkmcnt(6)
	v_mfma_f32_16x16x32_bf16 v[2:5], v[14:17], v[82:85], 0
	v_mfma_f32_16x16x32_bf16 v[6:9], v[30:33], v[82:85], 0
	s_waitcnt lgkmcnt(4)
	v_mfma_f32_16x16x32_bf16 v[2:5], v[18:21], v[86:89], v[2:5]
	v_mfma_f32_16x16x32_bf16 v[6:9], v[34:37], v[86:89], v[6:9]
	s_waitcnt lgkmcnt(2)
	v_mfma_f32_16x16x32_bf16 v[2:5], v[22:25], v[90:93], v[2:5]
	v_mfma_f32_16x16x32_bf16 v[6:9], v[38:41], v[90:93], v[6:9]
	s_waitcnt lgkmcnt(0)
	v_mfma_f32_16x16x32_bf16 v[2:5], v[26:29], v[94:97], v[2:5]
	v_mfma_f32_16x16x32_bf16 v[6:9], v[42:45], v[94:97], v[6:9]
	s_nop 3
	v_ashrrev_i32_e32 v11, 31, v0
	v_or_b32_e32 v10, v0, v140
	v_lshl_add_u64 v[12:13], v[10:11], 0, v[164:165]
	v_lshlrev_b64 v[12:13], 12, v[12:13]
	v_lshl_add_u64 v[12:13], v[162:163], 0, v[12:13]
	v_add_co_u32_e32 v14, vcc, s23, v12
	global_store_dword v[12:13], v2, off
	s_nop 0
	v_addc_co_u32_e32 v15, vcc, 0, v13, vcc
	v_add_co_u32_e32 v2, vcc, s20, v12
	global_store_dword v[14:15], v3, off offset:-4096
	global_store_dword v[14:15], v4, off
	v_addc_co_u32_e32 v3, vcc, 0, v13, vcc
	global_store_dword v[2:3], v5, off
	v_lshl_add_u64 v[2:3], v[10:11], 0, v[166:167]
	v_lshlrev_b64 v[2:3], 12, v[2:3]
	v_lshl_add_u64 v[2:3], v[162:163], 0, v[2:3]
	v_add_co_u32_e32 v4, vcc, s23, v2
	global_store_dword v[2:3], v6, off
	s_nop 0
	v_addc_co_u32_e32 v5, vcc, 0, v3, vcc
	v_add_co_u32_e32 v2, vcc, 0x3000, v2
	global_store_dword v[4:5], v7, off offset:-4096
	global_store_dword v[4:5], v8, off
	v_addc_co_u32_e32 v3, vcc, 0, v3, vcc
	global_store_dword v[2:3], v9, off
	s_waitcnt vmcnt(8)
	v_mov_b64_e32 v[8:9], v[102:103]
	v_mov_b64_e32 v[4:5], v[98:99]
	v_cmp_eq_u32_e32 vcc, s28, v149
	v_mov_b64_e32 v[10:11], v[104:105]
	v_mov_b64_e32 v[6:7], v[100:101]
	v_mov_b64_e32 v[102:103], v[106:107]
	v_mov_b64_e32 v[98:99], v[110:111]
	s_or_b64 s[2:3], vcc, s[2:3]
	v_mov_b64_e32 v[104:105], v[108:109]
	v_mov_b64_e32 v[100:101], v[112:113]
	s_andn2_b64 exec, exec, s[2:3]
	s_cbranch_execz .LBB0_106

.LBB0_102:
	s_or_b64 exec, exec, s[20:21]
	s_waitcnt vmcnt(2)
	v_cvt_pk_bf16_f32 v18, v8, v9
	v_cvt_pk_bf16_f32 v19, v10, v11
	v_cvt_pk_bf16_f32 v20, v4, v5
	v_cvt_pk_bf16_f32 v21, v6, v7
	v_pk_mul_f32 v[178:179], v[158:159], v[178:179] op_sel_hi:[1,0]
	v_pk_mul_f32 v[176:177], v[160:161], v[176:177] op_sel_hi:[1,0]
	v_mfma_f32_32x32x16_bf16 v[34:49], v[18:21], v[66:69], 0
	v_fma_f32 v184, v152, v182, -v178
	v_fma_f32 v185, v153, v183, -v179
	v_fma_f32 v178, v152, v182, v178
	v_fma_f32 v179, v153, v182, v179
	v_fma_f32 v182, v154, v180, -v176
	v_fma_f32 v183, v155, v181, -v177
	v_pk_fma_f32 v[176:177], v[154:155], v[180:181], v[176:177] op_sel_hi:[1,0,1]
	v_mov_b32_e32 v185, v179
	v_mov_b32_e32 v183, v177
	v_add_u32_e32 v212, 0xe00, v207
	v_mfma_f32_32x32x16_bf16 v[2:17], v[18:21], v[70:73], 0
	v_add_u32_e32 v180, 0xc00, v207
	v_add_u32_e32 v213, 0xa00, v207
	v_add_u32_e32 v211, 0x800, v207
	v_add_u32_e32 v0, 0x400, v207
	v_mfma_f32_32x32x16_bf16 v[50:65], v[18:21], v[74:77], 0
	v_mfma_f32_32x32x16_bf16 v[18:33], v[18:21], v[78:81], 0
	s_and_saveexec_b64 s[20:21], s[42:43]
	s_xor_b64 s[20:21], exec, s[20:21]
	s_cbranch_execz .LBB0_104
	s_nop 7
	v_add_f32_e32 v49, v184, v49
	v_add_f32_e32 v17, v182, v17
	v_add_f32_e32 v65, v185, v65
	v_add_f32_e32 v33, v183, v33
	v_cvt_pk_bf16_f32 v184, v49, v65
	v_cvt_pk_bf16_f32 v185, v17, v33
	ds_write_b32 v207, v184 offset:4080
	ds_write_b32 v207, v185 offset:4208
	v_fmac_f32_e32 v48, v152, v49
	v_fmac_f32_e32 v64, v152, v65
	v_fmac_f32_e32 v16, v154, v17
	v_fmac_f32_e32 v32, v154, v33
	v_fma_f32 v48, -v153, v65, v48
	v_fmac_f32_e32 v64, v153, v49
	v_fma_f32 v16, -v155, v33, v16
	v_fmac_f32_e32 v32, v155, v17
	v_cvt_pk_bf16_f32 v184, v48, v64
	v_cvt_pk_bf16_f32 v185, v16, v32
	ds_write_b32 v207, v184 offset:3808
	ds_write_b32 v207, v185 offset:3936
	v_fmac_f32_e32 v47, v152, v48
	v_fmac_f32_e32 v63, v152, v64
	v_fmac_f32_e32 v15, v154, v16
	v_fmac_f32_e32 v31, v154, v32
	v_fma_f32 v47, -v153, v64, v47
	v_fmac_f32_e32 v63, v153, v48
	v_fma_f32 v15, -v155, v32, v15
	v_fmac_f32_e32 v31, v155, v16
	v_cvt_pk_bf16_f32 v184, v47, v63
	v_cvt_pk_bf16_f32 v185, v15, v31
	ds_write_b32 v207, v184 offset:3536
	ds_write_b32 v207, v185 offset:3664
	v_fmac_f32_e32 v46, v152, v47
	v_fmac_f32_e32 v62, v152, v63
	v_fmac_f32_e32 v14, v154, v15
	v_fmac_f32_e32 v30, v154, v31
	v_fma_f32 v46, -v153, v63, v46
	v_fmac_f32_e32 v62, v153, v47
	v_fma_f32 v14, -v155, v31, v14
	v_fmac_f32_e32 v30, v155, v15
	v_cvt_pk_bf16_f32 v184, v46, v62
	v_cvt_pk_bf16_f32 v185, v14, v30
	ds_write_b32 v207, v184 offset:3264
	ds_write_b32 v207, v185 offset:3392
	v_fmac_f32_e32 v45, v152, v46
	v_fmac_f32_e32 v61, v152, v62
	v_fmac_f32_e32 v13, v154, v14
	v_fmac_f32_e32 v29, v154, v30
	v_fma_f32 v45, -v153, v62, v45
	v_fmac_f32_e32 v61, v153, v46
	v_fma_f32 v13, -v155, v30, v13
	v_fmac_f32_e32 v29, v155, v14
	v_cvt_pk_bf16_f32 v184, v45, v61
	v_cvt_pk_bf16_f32 v185, v13, v29
	ds_write_b32 v207, v184 offset:2992
	ds_write_b32 v207, v185 offset:3120
	v_fmac_f32_e32 v44, v152, v45
	v_fmac_f32_e32 v60, v152, v61
	v_fmac_f32_e32 v12, v154, v13
	v_fmac_f32_e32 v28, v154, v29
	v_fma_f32 v44, -v153, v61, v44
	v_fmac_f32_e32 v60, v153, v45
	v_fma_f32 v12, -v155, v29, v12
	v_fmac_f32_e32 v28, v155, v13
	v_cvt_pk_bf16_f32 v184, v44, v60
	v_cvt_pk_bf16_f32 v185, v12, v28
	ds_write_b32 v207, v184 offset:2720
	ds_write_b32 v207, v185 offset:2848
	v_fmac_f32_e32 v43, v152, v44
	v_fmac_f32_e32 v59, v152, v60
	v_fmac_f32_e32 v11, v154, v12
	v_fmac_f32_e32 v27, v154, v28
	v_fma_f32 v43, -v153, v60, v43
	v_fmac_f32_e32 v59, v153, v44
	v_fma_f32 v11, -v155, v28, v11
	v_fmac_f32_e32 v27, v155, v12
	v_cvt_pk_bf16_f32 v184, v43, v59
	v_cvt_pk_bf16_f32 v185, v11, v27
	ds_write_b32 v207, v184 offset:2448
	ds_write_b32 v207, v185 offset:2576
	v_fmac_f32_e32 v42, v152, v43
	v_fmac_f32_e32 v58, v152, v59
	v_fmac_f32_e32 v10, v154, v11
	v_fmac_f32_e32 v26, v154, v27
	v_fma_f32 v42, -v153, v59, v42
	v_fmac_f32_e32 v58, v153, v43
	v_fma_f32 v10, -v155, v27, v10
	v_fmac_f32_e32 v26, v155, v11
	v_cvt_pk_bf16_f32 v184, v42, v58
	v_cvt_pk_bf16_f32 v185, v10, v26
	ds_write_b32 v207, v184 offset:2176
	ds_write_b32 v207, v185 offset:2304
	v_fmac_f32_e32 v41, v152, v42
	v_fmac_f32_e32 v57, v152, v58
	v_fmac_f32_e32 v9, v154, v10
	v_fmac_f32_e32 v25, v154, v26
	v_fma_f32 v41, -v153, v58, v41
	v_fmac_f32_e32 v57, v153, v42
	v_fma_f32 v9, -v155, v26, v9
	v_fmac_f32_e32 v25, v155, v10
	v_cvt_pk_bf16_f32 v184, v41, v57
	v_cvt_pk_bf16_f32 v185, v9, v25
	ds_write_b32 v207, v184 offset:1904
	ds_write_b32 v207, v185 offset:2032
	v_fmac_f32_e32 v40, v152, v41
	v_fmac_f32_e32 v56, v152, v57
	v_fmac_f32_e32 v8, v154, v9
	v_fmac_f32_e32 v24, v154, v25
	v_fma_f32 v40, -v153, v57, v40
	v_fmac_f32_e32 v56, v153, v41
	v_fma_f32 v8, -v155, v25, v8
	v_fmac_f32_e32 v24, v155, v9
	v_cvt_pk_bf16_f32 v184, v40, v56
	v_cvt_pk_bf16_f32 v185, v8, v24
	ds_write_b32 v207, v184 offset:1632
	ds_write_b32 v207, v185 offset:1760
	v_fmac_f32_e32 v39, v152, v40
	v_fmac_f32_e32 v55, v152, v56
	v_fmac_f32_e32 v7, v154, v8
	v_fmac_f32_e32 v23, v154, v24
	v_fma_f32 v39, -v153, v56, v39
	v_fmac_f32_e32 v55, v153, v40
	v_fma_f32 v7, -v155, v24, v7
	v_fmac_f32_e32 v23, v155, v8
	v_cvt_pk_bf16_f32 v184, v39, v55
	v_cvt_pk_bf16_f32 v185, v7, v23
	ds_write_b32 v207, v184 offset:1360
	ds_write_b32 v207, v185 offset:1488
	v_fmac_f32_e32 v38, v152, v39
	v_fmac_f32_e32 v54, v152, v55
	v_fmac_f32_e32 v6, v154, v7
	v_fmac_f32_e32 v22, v154, v23
	v_fma_f32 v38, -v153, v55, v38
	v_fmac_f32_e32 v54, v153, v39
	v_fma_f32 v6, -v155, v23, v6
	v_fmac_f32_e32 v22, v155, v7
	v_cvt_pk_bf16_f32 v184, v38, v54
	v_cvt_pk_bf16_f32 v185, v6, v22
	ds_write_b32 v207, v184 offset:1088
	ds_write_b32 v207, v185 offset:1216
	v_fmac_f32_e32 v37, v152, v38
	v_fmac_f32_e32 v53, v152, v54
	v_fmac_f32_e32 v5, v154, v6
	v_fmac_f32_e32 v21, v154, v22
	v_fma_f32 v37, -v153, v54, v37
	v_fmac_f32_e32 v53, v153, v38
	v_fma_f32 v5, -v155, v22, v5
	v_fmac_f32_e32 v21, v155, v6
	v_cvt_pk_bf16_f32 v184, v37, v53
	v_cvt_pk_bf16_f32 v185, v5, v21
	ds_write_b32 v207, v184 offset:816
	ds_write_b32 v207, v185 offset:944
	v_fmac_f32_e32 v36, v152, v37
	v_fmac_f32_e32 v52, v152, v53
	v_fmac_f32_e32 v4, v154, v5
	v_fmac_f32_e32 v20, v154, v21
	v_fma_f32 v36, -v153, v53, v36
	v_fmac_f32_e32 v52, v153, v37
	v_fma_f32 v4, -v155, v21, v4
	v_fmac_f32_e32 v20, v155, v5
	v_cvt_pk_bf16_f32 v184, v36, v52
	v_cvt_pk_bf16_f32 v185, v4, v20
	ds_write_b32 v207, v184 offset:544
	ds_write_b32 v207, v185 offset:672
	v_fmac_f32_e32 v35, v152, v36
	v_fmac_f32_e32 v51, v152, v52
	v_fmac_f32_e32 v3, v154, v4
	v_fmac_f32_e32 v19, v154, v20
	v_fma_f32 v35, -v153, v52, v35
	v_fmac_f32_e32 v51, v153, v36
	v_fma_f32 v3, -v155, v20, v3
	v_fmac_f32_e32 v19, v155, v4
	v_cvt_pk_bf16_f32 v184, v35, v51
	v_cvt_pk_bf16_f32 v185, v3, v19
	ds_write_b32 v207, v184 offset:272
	ds_write_b32 v207, v185 offset:400
	v_fmac_f32_e32 v34, v152, v35
	v_fmac_f32_e32 v50, v152, v51
	v_fmac_f32_e32 v2, v154, v3
	v_fmac_f32_e32 v18, v154, v19
	v_fma_f32 v34, -v153, v51, v34
	v_fmac_f32_e32 v50, v153, v35
	v_fma_f32 v2, -v155, v19, v2
	v_fmac_f32_e32 v18, v155, v3
	v_cvt_pk_bf16_f32 v184, v34, v50
	v_cvt_pk_bf16_f32 v185, v2, v18
	ds_write_b32 v207, v184 offset:0
	ds_write_b32 v207, v185 offset:128
	v_mov_b32_e32 v179, v34
	v_mov_b32_e32 v178, v50
	v_mov_b32_e32 v177, v2
	v_mov_b32_e32 v176, v18
.LBB0_104:
	s_andn2_saveexec_b64 s[20:21], s[20:21]
	s_cbranch_execz .LBB0_99
	s_nop 7
	v_add_f32_e32 v34, v184, v34
	v_add_f32_e32 v2, v182, v2
	v_add_f32_e32 v50, v185, v50
	v_add_f32_e32 v18, v183, v18
	v_cvt_pk_bf16_f32 v184, v34, v50
	v_cvt_pk_bf16_f32 v185, v2, v18
	ds_write_b32 v207, v184 offset:0
	ds_write_b32 v207, v185 offset:128
	v_fmac_f32_e32 v35, v152, v34
	v_fmac_f32_e32 v51, v152, v50
	v_fmac_f32_e32 v3, v154, v2
	v_fmac_f32_e32 v19, v154, v18
	v_fma_f32 v35, -v153, v50, v35
	v_fmac_f32_e32 v51, v153, v34
	v_fma_f32 v3, -v155, v18, v3
	v_fmac_f32_e32 v19, v155, v2
	v_cvt_pk_bf16_f32 v184, v35, v51
	v_cvt_pk_bf16_f32 v185, v3, v19
	ds_write_b32 v207, v184 offset:272
	ds_write_b32 v207, v185 offset:400
	v_fmac_f32_e32 v36, v152, v35
	v_fmac_f32_e32 v52, v152, v51
	v_fmac_f32_e32 v4, v154, v3
	v_fmac_f32_e32 v20, v154, v19
	v_fma_f32 v36, -v153, v51, v36
	v_fmac_f32_e32 v52, v153, v35
	v_fma_f32 v4, -v155, v19, v4
	v_fmac_f32_e32 v20, v155, v3
	v_cvt_pk_bf16_f32 v184, v36, v52
	v_cvt_pk_bf16_f32 v185, v4, v20
	ds_write_b32 v207, v184 offset:544
	ds_write_b32 v207, v185 offset:672
	v_fmac_f32_e32 v37, v152, v36
	v_fmac_f32_e32 v53, v152, v52
	v_fmac_f32_e32 v5, v154, v4
	v_fmac_f32_e32 v21, v154, v20
	v_fma_f32 v37, -v153, v52, v37
	v_fmac_f32_e32 v53, v153, v36
	v_fma_f32 v5, -v155, v20, v5
	v_fmac_f32_e32 v21, v155, v4
	v_cvt_pk_bf16_f32 v184, v37, v53
	v_cvt_pk_bf16_f32 v185, v5, v21
	ds_write_b32 v207, v184 offset:816
	ds_write_b32 v207, v185 offset:944
	v_fmac_f32_e32 v38, v152, v37
	v_fmac_f32_e32 v54, v152, v53
	v_fmac_f32_e32 v6, v154, v5
	v_fmac_f32_e32 v22, v154, v21
	v_fma_f32 v38, -v153, v53, v38
	v_fmac_f32_e32 v54, v153, v37
	v_fma_f32 v6, -v155, v21, v6
	v_fmac_f32_e32 v22, v155, v5
	v_cvt_pk_bf16_f32 v184, v38, v54
	v_cvt_pk_bf16_f32 v185, v6, v22
	ds_write_b32 v207, v184 offset:1088
	ds_write_b32 v207, v185 offset:1216
	v_fmac_f32_e32 v39, v152, v38
	v_fmac_f32_e32 v55, v152, v54
	v_fmac_f32_e32 v7, v154, v6
	v_fmac_f32_e32 v23, v154, v22
	v_fma_f32 v39, -v153, v54, v39
	v_fmac_f32_e32 v55, v153, v38
	v_fma_f32 v7, -v155, v22, v7
	v_fmac_f32_e32 v23, v155, v6
	v_cvt_pk_bf16_f32 v184, v39, v55
	v_cvt_pk_bf16_f32 v185, v7, v23
	ds_write_b32 v207, v184 offset:1360
	ds_write_b32 v207, v185 offset:1488
	v_fmac_f32_e32 v40, v152, v39
	v_fmac_f32_e32 v56, v152, v55
	v_fmac_f32_e32 v8, v154, v7
	v_fmac_f32_e32 v24, v154, v23
	v_fma_f32 v40, -v153, v55, v40
	v_fmac_f32_e32 v56, v153, v39
	v_fma_f32 v8, -v155, v23, v8
	v_fmac_f32_e32 v24, v155, v7
	v_cvt_pk_bf16_f32 v184, v40, v56
	v_cvt_pk_bf16_f32 v185, v8, v24
	ds_write_b32 v207, v184 offset:1632
	ds_write_b32 v207, v185 offset:1760
	v_fmac_f32_e32 v41, v152, v40
	v_fmac_f32_e32 v57, v152, v56
	v_fmac_f32_e32 v9, v154, v8
	v_fmac_f32_e32 v25, v154, v24
	v_fma_f32 v41, -v153, v56, v41
	v_fmac_f32_e32 v57, v153, v40
	v_fma_f32 v9, -v155, v24, v9
	v_fmac_f32_e32 v25, v155, v8
	v_cvt_pk_bf16_f32 v184, v41, v57
	v_cvt_pk_bf16_f32 v185, v9, v25
	ds_write_b32 v207, v184 offset:1904
	ds_write_b32 v207, v185 offset:2032
	v_fmac_f32_e32 v42, v152, v41
	v_fmac_f32_e32 v58, v152, v57
	v_fmac_f32_e32 v10, v154, v9
	v_fmac_f32_e32 v26, v154, v25
	v_fma_f32 v42, -v153, v57, v42
	v_fmac_f32_e32 v58, v153, v41
	v_fma_f32 v10, -v155, v25, v10
	v_fmac_f32_e32 v26, v155, v9
	v_cvt_pk_bf16_f32 v184, v42, v58
	v_cvt_pk_bf16_f32 v185, v10, v26
	ds_write_b32 v207, v184 offset:2176
	ds_write_b32 v207, v185 offset:2304
	v_fmac_f32_e32 v43, v152, v42
	v_fmac_f32_e32 v59, v152, v58
	v_fmac_f32_e32 v11, v154, v10
	v_fmac_f32_e32 v27, v154, v26
	v_fma_f32 v43, -v153, v58, v43
	v_fmac_f32_e32 v59, v153, v42
	v_fma_f32 v11, -v155, v26, v11
	v_fmac_f32_e32 v27, v155, v10
	v_cvt_pk_bf16_f32 v184, v43, v59
	v_cvt_pk_bf16_f32 v185, v11, v27
	ds_write_b32 v207, v184 offset:2448
	ds_write_b32 v207, v185 offset:2576
	v_fmac_f32_e32 v44, v152, v43
	v_fmac_f32_e32 v60, v152, v59
	v_fmac_f32_e32 v12, v154, v11
	v_fmac_f32_e32 v28, v154, v27
	v_fma_f32 v44, -v153, v59, v44
	v_fmac_f32_e32 v60, v153, v43
	v_fma_f32 v12, -v155, v27, v12
	v_fmac_f32_e32 v28, v155, v11
	v_cvt_pk_bf16_f32 v184, v44, v60
	v_cvt_pk_bf16_f32 v185, v12, v28
	ds_write_b32 v207, v184 offset:2720
	ds_write_b32 v207, v185 offset:2848
	v_fmac_f32_e32 v45, v152, v44
	v_fmac_f32_e32 v61, v152, v60
	v_fmac_f32_e32 v13, v154, v12
	v_fmac_f32_e32 v29, v154, v28
	v_fma_f32 v45, -v153, v60, v45
	v_fmac_f32_e32 v61, v153, v44
	v_fma_f32 v13, -v155, v28, v13
	v_fmac_f32_e32 v29, v155, v12
	v_cvt_pk_bf16_f32 v184, v45, v61
	v_cvt_pk_bf16_f32 v185, v13, v29
	ds_write_b32 v207, v184 offset:2992
	ds_write_b32 v207, v185 offset:3120
	v_fmac_f32_e32 v46, v152, v45
	v_fmac_f32_e32 v62, v152, v61
	v_fmac_f32_e32 v14, v154, v13
	v_fmac_f32_e32 v30, v154, v29
	v_fma_f32 v46, -v153, v61, v46
	v_fmac_f32_e32 v62, v153, v45
	v_fma_f32 v14, -v155, v29, v14
	v_fmac_f32_e32 v30, v155, v13
	v_cvt_pk_bf16_f32 v184, v46, v62
	v_cvt_pk_bf16_f32 v185, v14, v30
	ds_write_b32 v207, v184 offset:3264
	ds_write_b32 v207, v185 offset:3392
	v_fmac_f32_e32 v47, v152, v46
	v_fmac_f32_e32 v63, v152, v62
	v_fmac_f32_e32 v15, v154, v14
	v_fmac_f32_e32 v31, v154, v30
	v_fma_f32 v47, -v153, v62, v47
	v_fmac_f32_e32 v63, v153, v46
	v_fma_f32 v15, -v155, v30, v15
	v_fmac_f32_e32 v31, v155, v14
	v_cvt_pk_bf16_f32 v184, v47, v63
	v_cvt_pk_bf16_f32 v185, v15, v31
	ds_write_b32 v207, v184 offset:3536
	ds_write_b32 v207, v185 offset:3664
	v_fmac_f32_e32 v48, v152, v47
	v_fmac_f32_e32 v64, v152, v63
	v_fmac_f32_e32 v16, v154, v15
	v_fmac_f32_e32 v32, v154, v31
	v_fma_f32 v48, -v153, v63, v48
	v_fmac_f32_e32 v64, v153, v47
	v_fma_f32 v16, -v155, v31, v16
	v_fmac_f32_e32 v32, v155, v15
	v_cvt_pk_bf16_f32 v184, v48, v64
	v_cvt_pk_bf16_f32 v185, v16, v32
	ds_write_b32 v207, v184 offset:3808
	ds_write_b32 v207, v185 offset:3936
	v_fmac_f32_e32 v49, v152, v48
	v_fmac_f32_e32 v65, v152, v64
	v_fmac_f32_e32 v17, v154, v16
	v_fmac_f32_e32 v33, v154, v32
	v_fma_f32 v49, -v153, v64, v49
	v_fmac_f32_e32 v65, v153, v48
	v_fma_f32 v17, -v155, v32, v17
	v_fmac_f32_e32 v33, v155, v16
	v_cvt_pk_bf16_f32 v184, v49, v65
	v_cvt_pk_bf16_f32 v185, v17, v33
	ds_write_b32 v207, v184 offset:4080
	ds_write_b32 v207, v185 offset:4208
	v_mov_b32_e32 v179, v49
	v_mov_b32_e32 v178, v65
	v_mov_b32_e32 v177, v17
	v_mov_b32_e32 v176, v33
	s_branch .LBB0_99
